# single-tile GEMMs of P3/P4: compiler's full vmcnt(0) drain before the first K-iteration removed (template's counted waits suffice, as in the down-tail copy)
# speedup vs baseline: 1.0067x; 1.0067x over previous
.LBB0_642:
	v_bfe_u32 v136, v202, 4, 2
	v_and_b32_e32 v12, 15, v202
	v_lshlrev_b32_e32 v13, 4, v136
	v_lshlrev_b32_e32 v14, 2, v202
	v_lshl_or_b32 v137, s8, 6, v12
	v_lshl_or_b32 v12, v12, 6, v13
	s_lshl_b32 s8, s8, 13
	v_and_b32_e32 v14, 32, v14
	s_and_b32 s26, s9, 3
	v_bitop3_b32 v12, v12, s8, v14 bitop3:0xde
	v_lshlrev_b32_e32 v15, 6, v202
	s_movk_i32 s8, 0x3c0
	v_readlane_b32 s45, v246, 0
	v_and_or_b32 v13, v15, s8, v13
	s_lshl_b32 s8, s26, 12
	s_add_i32 s47, s45, 0x18000
	v_bitop3_b32 v13, s8, v13, v14 bitop3:0xf6
	s_add_i32 s36, s47, s11
	s_mov_b64 s[8:9], 0x80
	v_lshl_add_u64 v[6:7], v[6:7], 0, s[8:9]
	s_mov_b32 m0, s36
	s_add_i32 s37, s36, 0x2000
	s_add_i32 s38, s29, 0x8000
	s_add_i32 s39, s29, 0xa000
	global_load_lds_dwordx4 v[6:7], off
	v_lshl_add_u64 v[4:5], v[4:5], 0, s[8:9]
	s_mov_b32 m0, s37
	s_add_u32 s16, s6, 0x40080
	global_load_lds_dwordx4 v[4:5], off
	v_lshl_add_u64 v[2:3], v[2:3], 0, s[8:9]
	s_mov_b32 m0, s38
	s_addc_u32 s17, s7, 0
	s_add_i32 s48, s45, 0x1c000
	global_load_lds_dwordx4 v[2:3], off
	v_lshl_add_u64 v[0:1], v[0:1], 0, s[8:9]
	s_mov_b32 m0, s39
	s_add_i32 s40, s48, s11
	global_load_lds_dwordx4 v[0:1], off
	v_lshl_add_u64 v[0:1], s[16:17], 0, v[130:131]
	s_mov_b32 m0, s40
	s_add_i32 s41, s40, 0x2000
	global_load_lds_dwordx4 v[0:1], off
	v_lshl_add_u64 v[0:1], s[16:17], 0, v[128:129]
	s_mov_b32 m0, s41
	s_lshl_b32 s10, s10, 19
	global_load_lds_dwordx4 v[0:1], off
	s_waitcnt vmcnt(8)
	s_barrier
	v_lshlrev_b32_e32 v0, 8, v202
	v_and_b32_e32 v0, 0xffff8000, v0
	v_lshlrev_b32_e32 v2, 11, v11
	s_add_u32 s10, s22, s10
	v_or3_b32 v0, v10, v0, v2
	s_addc_u32 s11, s23, 0
	v_add_u32_e32 v0, v0, v9
	v_mov_b32_e32 v1, v131
	v_lshl_add_u64 v[0:1], s[10:11], 0, v[0:1]
	s_mov_b64 s[16:17], 0x159e4080
	v_lshl_add_u64 v[132:133], v[0:1], 0, s[16:17]
	v_lshlrev_b32_e32 v0, 4, v8
	v_and_b32_e32 v0, 0xffff8000, v0
	v_or3_b32 v0, v10, v0, v2
	s_add_u32 s12, s22, s12
	s_waitcnt vmcnt(6)
	v_add_u32_e32 v0, v0, v9
	v_mov_b32_e32 v1, v131
	s_addc_u32 s13, s23, s13
	v_lshl_add_u64 v[0:1], s[10:11], 0, v[0:1]
	s_add_u32 s42, s12, 0x580100
	v_lshl_add_u64 v[134:135], v[0:1], 0, s[16:17]
	s_addc_u32 s43, s13, 0
	s_mov_b32 s44, -2
	s_mov_b64 s[12:13], 0
	v_add_u32_e32 v138, s14, v13
	v_add_u32_e32 v139, s45, v12
	s_add_i32 s45, s29, 0xc000
	s_add_i32 s46, s29, 0xe000
	v_add_u32_e32 v140, s15, v13
	v_add_u32_e32 v141, s47, v13
	v_add_u32_e32 v142, s48, v13
	v_mov_b32_e32 v0, v131
	v_mov_b32_e32 v1, v131
	v_mov_b32_e32 v2, v131
	v_mov_b32_e32 v3, v131
	v_mov_b32_e32 v4, v131
	v_mov_b32_e32 v5, v131
	v_mov_b32_e32 v6, v131
	v_mov_b32_e32 v7, v131
	v_mov_b32_e32 v16, v131
	v_mov_b32_e32 v17, v131
	v_mov_b32_e32 v18, v131
	v_mov_b32_e32 v19, v131
	v_mov_b32_e32 v20, v131
	s_waitcnt lgkmcnt(0)
	v_mov_b32_e32 v21, v131
	v_mov_b32_e32 v22, v131
	v_mov_b32_e32 v23, v131
	v_mov_b32_e32 v32, v131
	v_mov_b32_e32 v33, v131
	v_mov_b32_e32 v34, v131
	v_mov_b32_e32 v35, v131
	v_mov_b32_e32 v36, v131
	v_mov_b32_e32 v37, v131
	v_mov_b32_e32 v38, v131
	v_mov_b32_e32 v39, v131
	v_mov_b32_e32 v48, v131
	v_mov_b32_e32 v49, v131
	v_mov_b32_e32 v50, v131
	v_mov_b32_e32 v51, v131
	v_mov_b32_e32 v52, v131
	v_mov_b32_e32 v53, v131
	v_mov_b32_e32 v54, v131
	v_mov_b32_e32 v55, v131
	v_mov_b32_e32 v8, v131
	v_mov_b32_e32 v9, v131
	v_mov_b32_e32 v10, v131
	v_mov_b32_e32 v11, v131
	v_mov_b32_e32 v12, v131
	v_mov_b32_e32 v13, v131
	v_mov_b32_e32 v14, v131
	v_mov_b32_e32 v15, v131
	v_mov_b32_e32 v24, v131
	v_mov_b32_e32 v25, v131
	v_mov_b32_e32 v26, v131
	v_mov_b32_e32 v27, v131
	v_mov_b32_e32 v28, v131
	v_mov_b32_e32 v29, v131
	v_mov_b32_e32 v30, v131
	v_mov_b32_e32 v31, v131
	v_mov_b32_e32 v40, v131
	v_mov_b32_e32 v41, v131
	v_mov_b32_e32 v42, v131
	v_mov_b32_e32 v43, v131
	v_mov_b32_e32 v44, v131
	v_mov_b32_e32 v45, v131
	v_mov_b32_e32 v46, v131
	v_mov_b32_e32 v47, v131
	v_mov_b32_e32 v56, v131
	v_mov_b32_e32 v57, v131
	v_mov_b32_e32 v58, v131
	v_mov_b32_e32 v59, v131
	v_mov_b32_e32 v60, v131
	v_mov_b32_e32 v61, v131
	v_mov_b32_e32 v62, v131
	v_mov_b32_e32 v63, v131
	v_mov_b32_e32 v64, v131
	v_mov_b32_e32 v65, v131
	v_mov_b32_e32 v66, v131
	v_mov_b32_e32 v67, v131
	v_mov_b32_e32 v68, v131
	v_mov_b32_e32 v69, v131
	v_mov_b32_e32 v70, v131
	v_mov_b32_e32 v71, v131
	v_mov_b32_e32 v80, v131
	v_mov_b32_e32 v81, v131
	v_mov_b32_e32 v82, v131
	v_mov_b32_e32 v83, v131
	v_mov_b32_e32 v84, v131
	v_mov_b32_e32 v85, v131
	v_mov_b32_e32 v86, v131
	v_mov_b32_e32 v87, v131
	v_mov_b32_e32 v96, v131
	v_mov_b32_e32 v97, v131
	v_mov_b32_e32 v98, v131
	v_mov_b32_e32 v99, v131
	v_mov_b32_e32 v100, v131
	v_mov_b32_e32 v101, v131
	v_mov_b32_e32 v102, v131
	v_mov_b32_e32 v103, v131
	v_mov_b32_e32 v112, v131
	v_mov_b32_e32 v113, v131
	v_mov_b32_e32 v114, v131
	v_mov_b32_e32 v115, v131
	v_mov_b32_e32 v116, v131
	v_mov_b32_e32 v117, v131
	v_mov_b32_e32 v118, v131
	v_mov_b32_e32 v119, v131
	v_mov_b32_e32 v72, v131
	v_mov_b32_e32 v73, v131
	v_mov_b32_e32 v74, v131
	v_mov_b32_e32 v75, v131
	v_mov_b32_e32 v76, v131
	v_mov_b32_e32 v77, v131
	v_mov_b32_e32 v78, v131
	v_mov_b32_e32 v79, v131
	v_mov_b32_e32 v88, v131
	v_mov_b32_e32 v89, v131
	v_mov_b32_e32 v90, v131
	v_mov_b32_e32 v91, v131
	v_mov_b32_e32 v92, v131
	v_mov_b32_e32 v93, v131
	v_mov_b32_e32 v94, v131
	v_mov_b32_e32 v95, v131
	v_mov_b32_e32 v104, v131
	v_mov_b32_e32 v105, v131
	v_mov_b32_e32 v106, v131
	v_mov_b32_e32 v107, v131
	v_mov_b32_e32 v108, v131
	v_mov_b32_e32 v109, v131
	v_mov_b32_e32 v110, v131
	v_mov_b32_e32 v111, v131
	v_mov_b32_e32 v120, v131
	v_mov_b32_e32 v121, v131
	v_mov_b32_e32 v122, v131
	v_mov_b32_e32 v123, v131
	v_mov_b32_e32 v124, v131
	v_mov_b32_e32 v125, v131
	v_mov_b32_e32 v126, v131
	v_mov_b32_e32 v127, v131
	s_barrier

.LBB0_773:
	v_bfe_u32 v141, v202, 4, 2
	v_and_b32_e32 v139, 15, v202
	v_lshlrev_b32_e32 v138, 4, v141
	v_lshlrev_b32_e32 v13, 2, v202
	v_lshl_or_b32 v142, s6, 6, v139
	v_lshl_or_b32 v12, v139, 6, v138
	s_lshl_b32 s6, s6, 13
	v_and_b32_e32 v13, 32, v13
	s_and_b32 s17, s7, 3
	v_bitop3_b32 v12, v12, s6, v13 bitop3:0xde
	v_lshlrev_b32_e32 v14, 6, v202
	s_movk_i32 s6, 0x3c0
	v_readlane_b32 s41, v246, 0
	v_and_or_b32 v14, v14, s6, v138
	s_lshl_b32 s6, s17, 12
	s_add_i32 s43, s41, 0x18000
	v_bitop3_b32 v13, s6, v14, v13 bitop3:0xf6
	s_add_i32 s31, s43, s9
	s_mov_b64 s[6:7], 0x80
	v_lshl_add_u64 v[6:7], v[6:7], 0, s[6:7]
	s_mov_b32 m0, s31
	s_add_i32 s33, s31, 0x2000
	s_add_i32 s34, s25, 0x8000
	s_add_i32 s35, s25, 0xa000
	global_load_lds_dwordx4 v[6:7], off
	v_lshl_add_u64 v[4:5], v[4:5], 0, s[6:7]
	s_mov_b32 m0, s33
	s_add_u32 s14, s4, 0x40080
	global_load_lds_dwordx4 v[4:5], off
	v_lshl_add_u64 v[2:3], v[2:3], 0, s[6:7]
	s_mov_b32 m0, s34
	s_addc_u32 s15, s5, 0
	s_add_i32 s44, s41, 0x1c000
	global_load_lds_dwordx4 v[2:3], off
	v_lshl_add_u64 v[0:1], v[0:1], 0, s[6:7]
	s_mov_b32 m0, s35
	s_add_i32 s36, s44, s9
	global_load_lds_dwordx4 v[0:1], off
	v_lshl_add_u64 v[0:1], s[14:15], 0, v[132:133]
	s_mov_b32 m0, s36
	s_add_i32 s37, s36, 0x2000
	global_load_lds_dwordx4 v[0:1], off
	v_lshl_add_u64 v[0:1], s[14:15], 0, v[130:131]
	s_mov_b32 m0, s37
	s_lshl_b32 s8, s8, 19
	global_load_lds_dwordx4 v[0:1], off
	s_waitcnt vmcnt(8)
	s_barrier
	v_lshlrev_b32_e32 v0, 8, v202
	v_and_b32_e32 v0, 0xffff8000, v0
	v_lshlrev_b32_e32 v2, 11, v11
	s_add_u32 s8, s22, s8
	v_or3_b32 v0, v10, v0, v2
	s_addc_u32 s9, s23, 0
	v_add_u32_e32 v0, v0, v9
	v_mov_b32_e32 v1, v133
	v_lshl_add_u64 v[0:1], s[8:9], 0, v[0:1]
	s_mov_b64 s[14:15], 0x5c40080
	v_lshl_add_u64 v[134:135], v[0:1], 0, s[14:15]
	v_lshlrev_b32_e32 v0, 4, v8
	v_and_b32_e32 v0, 0xffff8000, v0
	v_or3_b32 v0, v10, v0, v2
	s_add_u32 s10, s22, s10
	s_waitcnt vmcnt(6)
	v_add_u32_e32 v0, v0, v9
	v_mov_b32_e32 v1, v133
	s_addc_u32 s11, s23, s11
	v_lshl_add_u64 v[0:1], s[8:9], 0, v[0:1]
	s_add_u32 s38, s10, 0x780100
	v_lshrrev_b32_e32 v140, 2, v202
	v_lshl_add_u64 v[136:137], v[0:1], 0, s[14:15]
	s_addc_u32 s39, s11, 0
	s_mov_b32 s40, -2
	s_mov_b64 s[10:11], 0
	v_add_u32_e32 v143, s12, v13
	v_add_u32_e32 v144, s41, v12
	s_add_i32 s41, s25, 0xc000
	s_add_i32 s42, s25, 0xe000
	v_add_u32_e32 v145, s13, v13
	v_add_u32_e32 v146, s43, v13
	v_add_u32_e32 v147, s44, v13
	v_mov_b32_e32 v0, v133
	v_mov_b32_e32 v1, v133
	v_mov_b32_e32 v2, v133
	v_mov_b32_e32 v3, v133
	v_mov_b32_e32 v4, v133
	v_mov_b32_e32 v5, v133
	v_mov_b32_e32 v6, v133
	v_mov_b32_e32 v7, v133
	v_mov_b32_e32 v16, v133
	v_mov_b32_e32 v17, v133
	v_mov_b32_e32 v18, v133
	v_mov_b32_e32 v19, v133
	v_mov_b32_e32 v20, v133
	v_mov_b32_e32 v21, v133
	v_mov_b32_e32 v22, v133
	v_mov_b32_e32 v23, v133
	v_mov_b32_e32 v32, v133
	v_mov_b32_e32 v33, v133
	v_mov_b32_e32 v34, v133
	v_mov_b32_e32 v35, v133
	v_mov_b32_e32 v36, v133
	v_mov_b32_e32 v37, v133
	v_mov_b32_e32 v38, v133
	v_mov_b32_e32 v39, v133
	v_mov_b32_e32 v48, v133
	v_mov_b32_e32 v49, v133
	v_mov_b32_e32 v50, v133
	v_mov_b32_e32 v51, v133
	v_mov_b32_e32 v52, v133
	v_mov_b32_e32 v53, v133
	v_mov_b32_e32 v54, v133
	v_mov_b32_e32 v55, v133
	v_mov_b32_e32 v8, v133
	v_mov_b32_e32 v9, v133
	v_mov_b32_e32 v10, v133
	v_mov_b32_e32 v11, v133
	v_mov_b32_e32 v12, v133
	v_mov_b32_e32 v13, v133
	v_mov_b32_e32 v14, v133
	v_mov_b32_e32 v15, v133
	v_mov_b32_e32 v24, v133
	v_mov_b32_e32 v25, v133
	v_mov_b32_e32 v26, v133
	v_mov_b32_e32 v27, v133
	v_mov_b32_e32 v28, v133
	v_mov_b32_e32 v29, v133
	v_mov_b32_e32 v30, v133
	v_mov_b32_e32 v31, v133
	v_mov_b32_e32 v40, v133
	v_mov_b32_e32 v41, v133
	v_mov_b32_e32 v42, v133
	v_mov_b32_e32 v43, v133
	v_mov_b32_e32 v44, v133
	v_mov_b32_e32 v45, v133
	v_mov_b32_e32 v46, v133
	v_mov_b32_e32 v47, v133
	v_mov_b32_e32 v56, v133
	v_mov_b32_e32 v57, v133
	v_mov_b32_e32 v58, v133
	v_mov_b32_e32 v59, v133
	v_mov_b32_e32 v60, v133
	v_mov_b32_e32 v61, v133
	v_mov_b32_e32 v62, v133
	v_mov_b32_e32 v63, v133
	v_mov_b32_e32 v64, v133
	v_mov_b32_e32 v65, v133
	v_mov_b32_e32 v66, v133
	v_mov_b32_e32 v67, v133
	v_mov_b32_e32 v68, v133
	v_mov_b32_e32 v69, v133
	v_mov_b32_e32 v70, v133
	v_mov_b32_e32 v71, v133
	v_mov_b32_e32 v80, v133
	v_mov_b32_e32 v81, v133
	v_mov_b32_e32 v82, v133
	v_mov_b32_e32 v83, v133
	v_mov_b32_e32 v84, v133
	v_mov_b32_e32 v85, v133
	v_mov_b32_e32 v86, v133
	v_mov_b32_e32 v87, v133
	v_mov_b32_e32 v96, v133
	v_mov_b32_e32 v97, v133
	v_mov_b32_e32 v98, v133
	v_mov_b32_e32 v99, v133
	v_mov_b32_e32 v100, v133
	v_mov_b32_e32 v101, v133
	v_mov_b32_e32 v102, v133
	v_mov_b32_e32 v103, v133
	v_mov_b32_e32 v112, v133
	v_mov_b32_e32 v113, v133
	v_mov_b32_e32 v114, v133
	v_mov_b32_e32 v115, v133
	v_mov_b32_e32 v116, v133
	v_mov_b32_e32 v117, v133
	v_mov_b32_e32 v118, v133
	v_mov_b32_e32 v119, v133
	v_mov_b32_e32 v72, v133
	v_mov_b32_e32 v73, v133
	v_mov_b32_e32 v74, v133
	v_mov_b32_e32 v75, v133
	v_mov_b32_e32 v76, v133
	v_mov_b32_e32 v77, v133
	v_mov_b32_e32 v78, v133
	v_mov_b32_e32 v79, v133
	v_mov_b32_e32 v88, v133
	v_mov_b32_e32 v89, v133
	v_mov_b32_e32 v90, v133
	v_mov_b32_e32 v91, v133
	v_mov_b32_e32 v92, v133
	v_mov_b32_e32 v93, v133
	v_mov_b32_e32 v94, v133
	v_mov_b32_e32 v95, v133
	v_mov_b32_e32 v104, v133
	v_mov_b32_e32 v105, v133
	v_mov_b32_e32 v106, v133
	v_mov_b32_e32 v107, v133
	v_mov_b32_e32 v108, v133
	v_mov_b32_e32 v109, v133
	v_mov_b32_e32 v110, v133
	v_mov_b32_e32 v111, v133
	v_mov_b32_e32 v120, v133
	v_mov_b32_e32 v121, v133
	v_mov_b32_e32 v122, v133
	v_mov_b32_e32 v123, v133
	v_mov_b32_e32 v124, v133
	v_mov_b32_e32 v125, v133
	v_mov_b32_e32 v126, v133
	v_mov_b32_e32 v127, v133
	s_barrier
.LBB0_774:
	s_add_u32 s12, s8, s10
	ds_read_b128 v[148:151], v143
	ds_read_b128 v[152:155], v143 offset:1024
	ds_read_b128 v[156:159], v143 offset:2048
	ds_read_b128 v[160:163], v143 offset:3072
	s_addc_u32 s13, s9, s11
	s_add_u32 s12, s12, 0x5c00100
	s_addc_u32 s13, s13, 0
	s_add_u32 s43, s38, s10
	s_addc_u32 s44, s39, s11
	s_cmpk_eq_i32 s10, 0x700
	s_cselect_b32 s15, s1, s13
	s_cselect_b32 s14, s0, s12
	s_cselect_b32 s13, s5, s44
	s_cselect_b32 s12, s4, s43
	s_mov_b32 m0, s41
	v_lshl_add_u64 v[196:197], v[134:135], 0, s[10:11]
	ds_read_b128 v[164:167], v144
	ds_read_b128 v[168:171], v144 offset:1024
	ds_read_b128 v[172:175], v144 offset:2048
	ds_read_b128 v[176:179], v144 offset:3072
	ds_read_b128 v[180:183], v144 offset:4096
	ds_read_b128 v[184:187], v144 offset:5120
	ds_read_b128 v[188:191], v144 offset:6144
	ds_read_b128 v[192:195], v144 offset:7168
	global_load_lds_dwordx4 v[196:197], off
	v_lshl_add_u64 v[196:197], v[136:137], 0, s[10:11]
	s_mov_b32 m0, s42
	s_nop 0
	global_load_lds_dwordx4 v[196:197], off
	ds_read_b128 v[196:199], v145
	ds_read_b128 v[204:207], v145 offset:1024
	ds_read_b128 v[208:211], v145 offset:2048
	ds_read_b128 v[212:215], v145 offset:3072
	s_waitcnt lgkmcnt(0)
	s_waitcnt vmcnt(8)
	s_barrier
	s_setprio 1
	v_mfma_f32_16x16x32_bf16 v[124:127], v[148:151], v[164:167], v[124:127]
	v_mfma_f32_16x16x32_bf16 v[120:123], v[156:159], v[164:167], v[120:123]
	v_mfma_f32_16x16x32_bf16 v[108:111], v[148:151], v[172:175], v[108:111]
	v_mfma_f32_16x16x32_bf16 v[104:107], v[156:159], v[172:175], v[104:107]
	v_mfma_f32_16x16x32_bf16 v[92:95], v[148:151], v[180:183], v[92:95]
	v_mfma_f32_16x16x32_bf16 v[88:91], v[156:159], v[180:183], v[88:91]
	v_mfma_f32_16x16x32_bf16 v[76:79], v[148:151], v[188:191], v[76:79]
	v_mfma_f32_16x16x32_bf16 v[72:75], v[156:159], v[188:191], v[72:75]
	v_mfma_f32_16x16x32_bf16 v[124:127], v[152:155], v[168:171], v[124:127]
	v_mfma_f32_16x16x32_bf16 v[120:123], v[160:163], v[168:171], v[120:123]
	v_mfma_f32_16x16x32_bf16 v[108:111], v[152:155], v[176:179], v[108:111]
	v_mfma_f32_16x16x32_bf16 v[104:107], v[160:163], v[176:179], v[104:107]
	v_mfma_f32_16x16x32_bf16 v[92:95], v[152:155], v[184:187], v[92:95]
	v_mfma_f32_16x16x32_bf16 v[88:91], v[160:163], v[184:187], v[88:91]
	v_mfma_f32_16x16x32_bf16 v[76:79], v[152:155], v[192:195], v[76:79]
	v_mfma_f32_16x16x32_bf16 v[72:75], v[160:163], v[192:195], v[72:75]
	v_mfma_f32_16x16x32_bf16 v[116:119], v[196:199], v[164:167], v[116:119]
	v_mfma_f32_16x16x32_bf16 v[112:115], v[208:211], v[164:167], v[112:115]
	v_mfma_f32_16x16x32_bf16 v[100:103], v[196:199], v[172:175], v[100:103]
	v_mfma_f32_16x16x32_bf16 v[96:99], v[208:211], v[172:175], v[96:99]
	v_mfma_f32_16x16x32_bf16 v[84:87], v[196:199], v[180:183], v[84:87]
	v_mfma_f32_16x16x32_bf16 v[80:83], v[208:211], v[180:183], v[80:83]
	v_mfma_f32_16x16x32_bf16 v[68:71], v[196:199], v[188:191], v[68:71]
	v_mfma_f32_16x16x32_bf16 v[64:67], v[208:211], v[188:191], v[64:67]
	v_mfma_f32_16x16x32_bf16 v[116:119], v[204:207], v[168:171], v[116:119]
	v_mfma_f32_16x16x32_bf16 v[112:115], v[212:215], v[168:171], v[112:115]
	v_mfma_f32_16x16x32_bf16 v[100:103], v[204:207], v[176:179], v[100:103]
	v_mfma_f32_16x16x32_bf16 v[96:99], v[212:215], v[176:179], v[96:99]
	v_mfma_f32_16x16x32_bf16 v[84:87], v[204:207], v[184:187], v[84:87]
	v_mfma_f32_16x16x32_bf16 v[80:83], v[212:215], v[184:187], v[80:83]
	v_mfma_f32_16x16x32_bf16 v[68:71], v[204:207], v[192:195], v[68:71]
	v_mfma_f32_16x16x32_bf16 v[64:67], v[212:215], v[192:195], v[64:67]
	s_setprio 0
	s_barrier
	ds_read_b128 v[164:167], v144 offset:16384
	ds_read_b128 v[168:171], v144 offset:17408
	ds_read_b128 v[172:175], v144 offset:18432
	ds_read_b128 v[176:179], v144 offset:19456
	ds_read_b128 v[180:183], v144 offset:20480
	ds_read_b128 v[184:187], v144 offset:21504
	ds_read_b128 v[188:191], v144 offset:22528
	ds_read_b128 v[192:195], v144 offset:23552
	s_mov_b32 m0, s19
	v_lshl_add_u64 v[200:201], s[12:13], 0, v[132:133]
	global_load_lds_dwordx4 v[200:201], off
	v_lshl_add_u64 v[216:217], s[12:13], 0, v[130:131]
	s_mov_b32 m0, s24
	s_nop 0
	global_load_lds_dwordx4 v[216:217], off
	s_mov_b32 m0, s25
	v_lshl_add_u64 v[218:219], s[14:15], 0, v[132:133]
	global_load_lds_dwordx4 v[218:219], off
	v_lshl_add_u64 v[220:221], s[14:15], 0, v[130:131]
	s_mov_b32 m0, s26
	s_nop 0
	global_load_lds_dwordx4 v[220:221], off
	s_add_u32 s44, s12, 0x40000
	s_addc_u32 s45, s13, 0
	s_mov_b32 m0, s27
	v_lshl_add_u64 v[248:249], s[44:45], 0, v[132:133]
	global_load_lds_dwordx4 v[248:249], off
	v_lshl_add_u64 v[248:249], s[44:45], 0, v[130:131]
	s_mov_b32 m0, s28
	s_nop 0
	global_load_lds_dwordx4 v[248:249], off
	s_waitcnt lgkmcnt(0)
	s_waitcnt vmcnt(8)
	s_barrier
	s_setprio 1
	v_mfma_f32_16x16x32_bf16 v[60:63], v[148:151], v[164:167], v[60:63]
	v_mfma_f32_16x16x32_bf16 v[56:59], v[156:159], v[164:167], v[56:59]
	v_mfma_f32_16x16x32_bf16 v[44:47], v[148:151], v[172:175], v[44:47]
	v_mfma_f32_16x16x32_bf16 v[40:43], v[156:159], v[172:175], v[40:43]
	v_mfma_f32_16x16x32_bf16 v[28:31], v[148:151], v[180:183], v[28:31]
	v_mfma_f32_16x16x32_bf16 v[24:27], v[156:159], v[180:183], v[24:27]
	v_mfma_f32_16x16x32_bf16 v[12:15], v[148:151], v[188:191], v[12:15]
	v_mfma_f32_16x16x32_bf16 v[8:11], v[156:159], v[188:191], v[8:11]
	v_mfma_f32_16x16x32_bf16 v[60:63], v[152:155], v[168:171], v[60:63]
	v_mfma_f32_16x16x32_bf16 v[56:59], v[160:163], v[168:171], v[56:59]
	v_mfma_f32_16x16x32_bf16 v[44:47], v[152:155], v[176:179], v[44:47]
	v_mfma_f32_16x16x32_bf16 v[40:43], v[160:163], v[176:179], v[40:43]
	v_mfma_f32_16x16x32_bf16 v[28:31], v[152:155], v[184:187], v[28:31]
	v_mfma_f32_16x16x32_bf16 v[24:27], v[160:163], v[184:187], v[24:27]
	v_mfma_f32_16x16x32_bf16 v[12:15], v[152:155], v[192:195], v[12:15]
	v_mfma_f32_16x16x32_bf16 v[8:11], v[160:163], v[192:195], v[8:11]
	v_mfma_f32_16x16x32_bf16 v[52:55], v[196:199], v[164:167], v[52:55]
	v_mfma_f32_16x16x32_bf16 v[48:51], v[208:211], v[164:167], v[48:51]
	v_mfma_f32_16x16x32_bf16 v[36:39], v[196:199], v[172:175], v[36:39]
	v_mfma_f32_16x16x32_bf16 v[32:35], v[208:211], v[172:175], v[32:35]
	v_mfma_f32_16x16x32_bf16 v[20:23], v[196:199], v[180:183], v[20:23]
	v_mfma_f32_16x16x32_bf16 v[16:19], v[208:211], v[180:183], v[16:19]
	v_mfma_f32_16x16x32_bf16 v[4:7], v[196:199], v[188:191], v[4:7]
	v_mfma_f32_16x16x32_bf16 v[0:3], v[208:211], v[188:191], v[0:3]
	v_mfma_f32_16x16x32_bf16 v[52:55], v[204:207], v[168:171], v[52:55]
	v_mfma_f32_16x16x32_bf16 v[48:51], v[212:215], v[168:171], v[48:51]
	v_mfma_f32_16x16x32_bf16 v[36:39], v[204:207], v[176:179], v[36:39]
	v_mfma_f32_16x16x32_bf16 v[32:35], v[212:215], v[176:179], v[32:35]
	v_mfma_f32_16x16x32_bf16 v[20:23], v[204:207], v[184:187], v[20:23]
	v_mfma_f32_16x16x32_bf16 v[16:19], v[212:215], v[184:187], v[16:19]
	v_mfma_f32_16x16x32_bf16 v[4:7], v[204:207], v[192:195], v[4:7]
	v_mfma_f32_16x16x32_bf16 v[0:3], v[212:215], v[192:195], v[0:3]
	s_setprio 0
	s_barrier
	ds_read_b128 v[148:151], v146
	ds_read_b128 v[152:155], v146 offset:1024
	ds_read_b128 v[156:159], v146 offset:2048
	ds_read_b128 v[160:163], v146 offset:3072
	s_add_u32 s14, s14, 0x40000
	s_addc_u32 s15, s15, 0
	s_mov_b32 m0, s29
	v_lshl_add_u64 v[196:197], s[14:15], 0, v[132:133]
	ds_read_b128 v[164:167], v144 offset:32768
	ds_read_b128 v[168:171], v144 offset:33792
	ds_read_b128 v[172:175], v144 offset:34816
	ds_read_b128 v[176:179], v144 offset:35840
	ds_read_b128 v[180:183], v144 offset:36864
	ds_read_b128 v[184:187], v144 offset:37888
	ds_read_b128 v[188:191], v144 offset:38912
	ds_read_b128 v[192:195], v144 offset:39936
	global_load_lds_dwordx4 v[196:197], off
	v_lshl_add_u64 v[196:197], s[14:15], 0, v[130:131]
	s_mov_b32 m0, s30
	s_nop 0
	global_load_lds_dwordx4 v[196:197], off
	ds_read_b128 v[196:199], v147
	ds_read_b128 v[204:207], v147 offset:1024
	ds_read_b128 v[208:211], v147 offset:2048
	ds_read_b128 v[212:215], v147 offset:3072
	s_waitcnt lgkmcnt(0)
	s_waitcnt vmcnt(8)
	s_barrier
	s_setprio 1
	v_mfma_f32_16x16x32_bf16 v[124:127], v[148:151], v[164:167], v[124:127]
	v_mfma_f32_16x16x32_bf16 v[120:123], v[156:159], v[164:167], v[120:123]
	v_mfma_f32_16x16x32_bf16 v[108:111], v[148:151], v[172:175], v[108:111]
	v_mfma_f32_16x16x32_bf16 v[104:107], v[156:159], v[172:175], v[104:107]
	v_mfma_f32_16x16x32_bf16 v[92:95], v[148:151], v[180:183], v[92:95]
	v_mfma_f32_16x16x32_bf16 v[88:91], v[156:159], v[180:183], v[88:91]
	v_mfma_f32_16x16x32_bf16 v[76:79], v[148:151], v[188:191], v[76:79]
	v_mfma_f32_16x16x32_bf16 v[72:75], v[156:159], v[188:191], v[72:75]
	v_mfma_f32_16x16x32_bf16 v[124:127], v[152:155], v[168:171], v[124:127]
	v_mfma_f32_16x16x32_bf16 v[120:123], v[160:163], v[168:171], v[120:123]
	v_mfma_f32_16x16x32_bf16 v[108:111], v[152:155], v[176:179], v[108:111]
	v_mfma_f32_16x16x32_bf16 v[104:107], v[160:163], v[176:179], v[104:107]
	v_mfma_f32_16x16x32_bf16 v[92:95], v[152:155], v[184:187], v[92:95]
	v_mfma_f32_16x16x32_bf16 v[88:91], v[160:163], v[184:187], v[88:91]
	v_mfma_f32_16x16x32_bf16 v[76:79], v[152:155], v[192:195], v[76:79]
	v_mfma_f32_16x16x32_bf16 v[72:75], v[160:163], v[192:195], v[72:75]
	v_mfma_f32_16x16x32_bf16 v[116:119], v[196:199], v[164:167], v[116:119]
	v_mfma_f32_16x16x32_bf16 v[112:115], v[208:211], v[164:167], v[112:115]
	v_mfma_f32_16x16x32_bf16 v[100:103], v[196:199], v[172:175], v[100:103]
	v_mfma_f32_16x16x32_bf16 v[96:99], v[208:211], v[172:175], v[96:99]
	v_mfma_f32_16x16x32_bf16 v[84:87], v[196:199], v[180:183], v[84:87]
	v_mfma_f32_16x16x32_bf16 v[80:83], v[208:211], v[180:183], v[80:83]
	v_mfma_f32_16x16x32_bf16 v[68:71], v[196:199], v[188:191], v[68:71]
	v_mfma_f32_16x16x32_bf16 v[64:67], v[208:211], v[188:191], v[64:67]
	v_mfma_f32_16x16x32_bf16 v[116:119], v[204:207], v[168:171], v[116:119]
	v_mfma_f32_16x16x32_bf16 v[112:115], v[212:215], v[168:171], v[112:115]
	v_mfma_f32_16x16x32_bf16 v[100:103], v[204:207], v[176:179], v[100:103]
	v_mfma_f32_16x16x32_bf16 v[96:99], v[212:215], v[176:179], v[96:99]
	v_mfma_f32_16x16x32_bf16 v[84:87], v[204:207], v[184:187], v[84:87]
	v_mfma_f32_16x16x32_bf16 v[80:83], v[212:215], v[184:187], v[80:83]
	v_mfma_f32_16x16x32_bf16 v[68:71], v[204:207], v[192:195], v[68:71]
	v_mfma_f32_16x16x32_bf16 v[64:67], v[212:215], v[192:195], v[64:67]
	s_setprio 0
	s_barrier
	ds_read_b128 v[164:167], v144 offset:49152
	ds_read_b128 v[168:171], v144 offset:50176
	ds_read_b128 v[172:175], v144 offset:51200
	ds_read_b128 v[176:179], v144 offset:52224
	ds_read_b128 v[180:183], v144 offset:53248
	ds_read_b128 v[184:187], v144 offset:54272
	ds_read_b128 v[188:191], v144 offset:55296
	ds_read_b128 v[192:195], v144 offset:56320
	s_mov_b32 m0, s31
	v_lshl_add_u64 v[200:201], v[200:201], 0, s[6:7]
	global_load_lds_dwordx4 v[200:201], off
	v_lshl_add_u64 v[200:201], v[216:217], 0, s[6:7]
	s_mov_b32 m0, s33
	s_nop 0
	global_load_lds_dwordx4 v[200:201], off
	s_mov_b32 m0, s34
	v_lshl_add_u64 v[200:201], v[218:219], 0, s[6:7]
	global_load_lds_dwordx4 v[200:201], off
	v_lshl_add_u64 v[200:201], v[220:221], 0, s[6:7]
	s_mov_b32 m0, s35
	s_nop 0
	global_load_lds_dwordx4 v[200:201], off
	s_add_u32 s12, s12, 0x40080
	s_addc_u32 s13, s13, 0
	s_mov_b32 m0, s36
	v_lshl_add_u64 v[248:249], s[12:13], 0, v[132:133]
	global_load_lds_dwordx4 v[248:249], off
	v_lshl_add_u64 v[248:249], s[12:13], 0, v[130:131]
	s_mov_b32 m0, s37
	s_nop 0
	global_load_lds_dwordx4 v[248:249], off
	s_waitcnt lgkmcnt(0)
	s_waitcnt vmcnt(8)
	s_barrier
	s_setprio 1
	v_mfma_f32_16x16x32_bf16 v[60:63], v[148:151], v[164:167], v[60:63]
	v_mfma_f32_16x16x32_bf16 v[56:59], v[156:159], v[164:167], v[56:59]
	v_mfma_f32_16x16x32_bf16 v[44:47], v[148:151], v[172:175], v[44:47]
	v_mfma_f32_16x16x32_bf16 v[40:43], v[156:159], v[172:175], v[40:43]
	v_mfma_f32_16x16x32_bf16 v[28:31], v[148:151], v[180:183], v[28:31]
	v_mfma_f32_16x16x32_bf16 v[24:27], v[156:159], v[180:183], v[24:27]
	v_mfma_f32_16x16x32_bf16 v[12:15], v[148:151], v[188:191], v[12:15]
	v_mfma_f32_16x16x32_bf16 v[8:11], v[156:159], v[188:191], v[8:11]
	v_mfma_f32_16x16x32_bf16 v[60:63], v[152:155], v[168:171], v[60:63]
	v_mfma_f32_16x16x32_bf16 v[56:59], v[160:163], v[168:171], v[56:59]
	v_mfma_f32_16x16x32_bf16 v[44:47], v[152:155], v[176:179], v[44:47]
	v_mfma_f32_16x16x32_bf16 v[40:43], v[160:163], v[176:179], v[40:43]
	v_mfma_f32_16x16x32_bf16 v[28:31], v[152:155], v[184:187], v[28:31]
	v_mfma_f32_16x16x32_bf16 v[24:27], v[160:163], v[184:187], v[24:27]
	v_mfma_f32_16x16x32_bf16 v[12:15], v[152:155], v[192:195], v[12:15]
	v_mfma_f32_16x16x32_bf16 v[8:11], v[160:163], v[192:195], v[8:11]
	v_mfma_f32_16x16x32_bf16 v[52:55], v[196:199], v[164:167], v[52:55]
	v_mfma_f32_16x16x32_bf16 v[48:51], v[208:211], v[164:167], v[48:51]
	v_mfma_f32_16x16x32_bf16 v[36:39], v[196:199], v[172:175], v[36:39]
	v_mfma_f32_16x16x32_bf16 v[32:35], v[208:211], v[172:175], v[32:35]
	v_mfma_f32_16x16x32_bf16 v[20:23], v[196:199], v[180:183], v[20:23]
	v_mfma_f32_16x16x32_bf16 v[16:19], v[208:211], v[180:183], v[16:19]
	v_mfma_f32_16x16x32_bf16 v[4:7], v[196:199], v[188:191], v[4:7]
	v_mfma_f32_16x16x32_bf16 v[0:3], v[208:211], v[188:191], v[0:3]
	v_mfma_f32_16x16x32_bf16 v[52:55], v[204:207], v[168:171], v[52:55]
	v_mfma_f32_16x16x32_bf16 v[48:51], v[212:215], v[168:171], v[48:51]
	v_mfma_f32_16x16x32_bf16 v[36:39], v[204:207], v[176:179], v[36:39]
	v_mfma_f32_16x16x32_bf16 v[32:35], v[212:215], v[176:179], v[32:35]
	v_mfma_f32_16x16x32_bf16 v[20:23], v[204:207], v[184:187], v[20:23]
	v_mfma_f32_16x16x32_bf16 v[16:19], v[212:215], v[184:187], v[16:19]
	v_mfma_f32_16x16x32_bf16 v[4:7], v[204:207], v[192:195], v[4:7]
	v_mfma_f32_16x16x32_bf16 v[0:3], v[212:215], v[192:195], v[0:3]
	s_setprio 0
	s_add_i32 s40, s40, 2
	s_add_u32 s10, s10, 0x100
	s_addc_u32 s11, s11, 0
	s_cmp_gt_u32 s40, 13
	s_barrier
	s_cbranch_scc0 .LBB0_774
	v_mul_u32_u24_e32 v130, 0x21000, v141
	v_mov_b32_e32 v133, 0
	v_lshlrev_b32_e32 v130, 2, v130
	v_mov_b32_e32 v131, v133
	v_lshl_add_u32 v132, s18, 8, v142
	v_lshl_add_u64 v[130:131], s[22:23], 0, v[130:131]
	v_lshl_add_u64 v[130:131], v[132:133], 2, v[130:131]
	s_mov_b64 s[0:1], 0x18ba4000
	v_lshl_add_u64 v[134:135], v[130:131], 0, s[0:1]
	s_mov_b32 s0, 0x18ba4000
	v_add_co_u32_e32 v136, vcc, s0, v130
	s_mov_b32 s0, 0x18bc5000
	s_nop 0
	v_addc_co_u32_e32 v137, vcc, 0, v131, vcc
	v_add_co_u32_e32 v142, vcc, s0, v130
	s_mov_b32 s0, 0x18be6000
	s_nop 0
	v_addc_co_u32_e32 v143, vcc, 0, v131, vcc
	v_add_co_u32_e32 v144, vcc, s0, v130
	s_mov_b32 s0, 0x18c07000
	s_nop 0
	v_addc_co_u32_e32 v145, vcc, 0, v131, vcc
	v_add_co_u32_e32 v130, vcc, s0, v130
	v_mov_b32_e32 v151, 0x358637bd
	s_nop 0
	v_addc_co_u32_e32 v131, vcc, 0, v131, vcc
	global_load_dword v146, v[142:143], off
	global_load_dword v150, v[142:143], off offset:64
	global_load_dword v149, v[144:145], off
	global_load_dword v152, v[144:145], off offset:64
	global_load_dword v147, v[130:131], off
	global_load_dword v153, v[130:131], off offset:64
	global_load_dword v148, v[136:137], off
	global_load_dword v154, v[134:135], off offset:64
	global_load_dword v155, v[134:135], off offset:128
	global_load_dword v156, v[142:143], off offset:128
	global_load_dword v157, v[144:145], off offset:128
	global_load_dword v158, v[130:131], off offset:128
	global_load_dword v159, v[134:135], off offset:192
	global_load_dword v160, v[142:143], off offset:192
	global_load_dword v161, v[144:145], off offset:192
	global_load_dword v162, v[130:131], off offset:192
	global_load_dword v163, v[134:135], off offset:512
	global_load_dword v164, v[142:143], off offset:512
	global_load_dword v165, v[144:145], off offset:512
	global_load_dword v166, v[130:131], off offset:512
	global_load_dword v167, v[134:135], off offset:576
	global_load_dword v168, v[142:143], off offset:576
	global_load_dword v169, v[144:145], off offset:576
	global_load_dword v170, v[130:131], off offset:576
	global_load_dword v171, v[134:135], off offset:640
	global_load_dword v172, v[142:143], off offset:640
	global_load_dword v173, v[144:145], off offset:640
	global_load_dword v174, v[130:131], off offset:640
	s_nop 0
	global_load_dword v135, v[134:135], off offset:704
	s_nop 0
	global_load_dword v142, v[142:143], off offset:704
	s_nop 0
	global_load_dword v143, v[144:145], off offset:704
	s_nop 0
	global_load_dword v144, v[130:131], off offset:704
	v_mbcnt_lo_u32_b32 v131, -1, 0
	v_mbcnt_hi_u32_b32 v131, -1, v131
	v_and_b32_e32 v136, 64, v131
	v_xor_b32_e32 v134, 16, v131
	v_add_u32_e32 v136, 64, v136
	v_xor_b32_e32 v137, 32, v131
	v_cmp_lt_i32_e64 s[0:1], v134, v136
	s_add_u32 s4, s22, 0x195cc000
	s_addc_u32 s5, s23, 0
	v_cndmask_b32_e64 v134, v131, v134, s[0:1]
	v_cmp_lt_i32_e64 s[0:1], v137, v136
	s_add_u32 s6, s22, 0x18fc4000
	s_addc_u32 s7, s23, 0
	v_cndmask_b32_e64 v136, v131, v137, s[0:1]
	v_lshlrev_b32_e32 v131, 2, v134
	v_lshlrev_b32_e32 v134, 2, v136
	s_lshl_b32 s8, s17, 6
	s_lshl_b32 s0, s2, 8
	v_lshlrev_b32_e32 v130, 3, v141
	s_or_b32 s0, s8, s0
	v_cmp_eq_u32_e32 vcc, 0, v141
	s_waitcnt vmcnt(0)
	v_pk_add_f32 v[136:137], v[148:149], v[146:147]
	s_nop 0
	v_add_f32_e32 v136, v136, v137
	ds_bpermute_b32 v137, v131, v136
	v_add_f32_e32 v145, v154, v150
	v_add_f32_e32 v147, v155, v156
	v_add_f32_e32 v148, v157, v158
	v_add_f32_e32 v147, v147, v148
	s_waitcnt lgkmcnt(0)
	v_add_f32_e32 v136, v136, v137
	ds_bpermute_b32 v137, v134, v136
	v_add_f32_e32 v149, v159, v160
	ds_bpermute_b32 v148, v131, v147
	v_or_b32_e32 v160, s0, v130
	v_add_f32_e32 v146, v152, v153
	s_waitcnt lgkmcnt(1)
	v_add_f32_e32 v136, v136, v137
	v_fmamk_f32 v136, v136, 0x3a800000, v151
	v_rsq_f32_e32 v154, v136
	v_add_f32_e32 v136, v161, v162
	v_add_f32_e32 v136, v149, v136
	ds_bpermute_b32 v137, v131, v136
	s_waitcnt lgkmcnt(1)
	v_add_f32_e32 v149, v147, v148
	v_add_f32_e32 v155, v171, v172
	v_add_f32_e32 v156, v173, v174
	v_add_f32_e32 v155, v155, v156
	s_waitcnt lgkmcnt(0)
	v_add_f32_e32 v147, v136, v137
	v_add_f32_e32 v136, v167, v168
	v_add_f32_e32 v137, v169, v170
	v_add_f32_e32 v135, v135, v142
	v_add_f32_e32 v142, v143, v144
	v_add_f32_e32 v136, v136, v137
	v_add_f32_e32 v135, v135, v142
	ds_bpermute_b32 v137, v131, v136
	ds_bpermute_b32 v156, v131, v155
	ds_bpermute_b32 v157, v131, v135
	v_pk_mul_f32 v[126:127], v[126:127], v[154:155] op_sel_hi:[1,0]
	v_pk_mul_f32 v[124:125], v[124:125], v[154:155] op_sel_hi:[1,0]
	s_waitcnt lgkmcnt(2)
	v_add_f32_e32 v143, v136, v137
	s_waitcnt lgkmcnt(1)
	v_add_f32_e32 v137, v155, v156
	s_waitcnt lgkmcnt(0)
	v_add_f32_e32 v135, v135, v157
	v_pk_mul_f32 v[122:123], v[122:123], v[154:155] op_sel_hi:[1,0]
	v_pk_mul_f32 v[120:121], v[120:121], v[154:155] op_sel_hi:[1,0]
	v_pk_mul_f32 v[118:119], v[118:119], v[154:155] op_sel_hi:[1,0]
	v_pk_mul_f32 v[156:157], v[116:117], v[154:155] op_sel_hi:[1,0]
	v_pk_mul_f32 v[158:159], v[114:115], v[154:155] op_sel_hi:[1,0]
	v_pk_mul_f32 v[154:155], v[112:113], v[154:155] op_sel_hi:[1,0]
	v_lshlrev_b64 v[112:113], 10, v[132:133]
	v_mul_f32_e32 v116, v125, v125
	v_mul_f32_e32 v117, v127, v127
	v_lshl_add_u64 v[114:115], s[4:5], 0, v[112:113]
	v_lshlrev_b32_e32 v112, 1, v160
	v_mov_b32_e32 v113, v133
	v_fmac_f32_e32 v116, v124, v124
	v_fmac_f32_e32 v117, v126, v126
	v_lshl_add_u64 v[160:161], v[114:115], 0, v[112:113]
	v_cvt_pk_bf16_f32 v114, v124, v125
	v_add_f32_e32 v116, v116, v117
	v_mul_f32_e32 v117, v121, v121
	v_mul_f32_e32 v124, v123, v123
	v_fmac_f32_e32 v117, v120, v120
	v_fmac_f32_e32 v124, v122, v122
	v_add_f32_e32 v145, v145, v146
	v_add_f32_e32 v117, v117, v124
	ds_bpermute_b32 v146, v131, v145
	v_add_f32_e32 v116, v116, v117
	v_mul_f32_e32 v117, v157, v157
	v_mul_f32_e32 v124, v119, v119
	v_fmac_f32_e32 v117, v156, v156
	v_fmac_f32_e32 v124, v118, v118
	v_add_f32_e32 v117, v117, v124
	v_mul_f32_e32 v124, v155, v155
	v_mul_f32_e32 v125, v159, v159
	v_fmac_f32_e32 v124, v154, v154
	v_fmac_f32_e32 v125, v158, v158
	v_add_f32_e32 v124, v124, v125
	s_waitcnt lgkmcnt(0)
	v_add_f32_e32 v152, v145, v146
	v_add_f32_e32 v145, v163, v164
	v_add_f32_e32 v146, v165, v166
	v_add_f32_e32 v117, v117, v124
	v_add_f32_e32 v145, v145, v146
	v_add_f32_e32 v124, v116, v117
	ds_bpermute_b32 v146, v131, v145
	ds_bpermute_b32 v125, v131, v124
	v_cvt_pk_bf16_f32 v115, v126, v127
	v_cvt_pk_bf16_f32 v116, v120, v121
	v_cvt_pk_bf16_f32 v117, v122, v123
	s_waitcnt lgkmcnt(1)
	v_add_f32_e32 v145, v145, v146
	global_store_dwordx4 v[160:161], v[114:117], off
	ds_bpermute_b32 v153, v134, v152
	ds_bpermute_b32 v150, v134, v149
	s_waitcnt lgkmcnt(2)
	v_add_f32_e32 v114, v124, v125
	ds_bpermute_b32 v148, v134, v147
	ds_bpermute_b32 v146, v134, v145
	ds_bpermute_b32 v144, v134, v143
	ds_bpermute_b32 v142, v134, v137
	ds_bpermute_b32 v136, v134, v135
	ds_bpermute_b32 v115, v134, v114
	s_and_b32 s0, s16, -4
	s_or_b32 s8, s17, s0
	s_mul_hi_u32 s2, s8, 0x21000
	s_mul_i32 s8, s8, 0x21000
	v_cvt_pk_bf16_f32 v116, v156, v157
	v_cvt_pk_bf16_f32 v117, v118, v119
	v_cvt_pk_bf16_f32 v118, v154, v155
	v_cvt_pk_bf16_f32 v119, v158, v159
	global_store_dwordx4 v[160:161], v[116:119], off offset:64
	s_and_saveexec_b64 s[0:1], vcc
	s_cbranch_execz .LBB0_777
	s_add_u32 s10, s6, s8
	s_addc_u32 s11, s7, s2
	v_lshl_add_u64 v[116:117], v[132:133], 2, s[10:11]
	s_waitcnt lgkmcnt(0)
	v_add_f32_e32 v114, v114, v115
	global_store_dword v[116:117], v114, off
